# gemm2/gemm3 epilogues: full vmcnt(0) drains replaced by exact counted waits
# speedup vs baseline: 1.0091x; 1.0014x over previous
;     __device__ __forceinline__ void operator()(const f32x4 (&acc)[2][2][4][2], const pg8::Unit& u, int wr, int wc, int fr_in, int fq_in) const {
;     ...
;             const int gr0 = grow(g, u.pm * 256), s = seq_of(gr0);
;             const float* xb = layer ? (const float*)out + (size_t)gr0 * 1024 : (gr0 < NPTOK ? xp + (size_t)gr0 * 1024 : xs + (size_t)(gr0 - NPTOK) * 1024);
;             float* ob = out + (size_t)gr0 * 1024;
;             const int rl0 = wr * 64 + fr;
;             f32x4 gv[2][2];
; #pragma unroll
;             for (int bj = 0; bj < 2; ++bj) { gv[bj][0] = *(const f32x4*)(bias + s * 3072 + 2048 + col0 + bj * 128) + 1.0f; gv[bj][1] = *(const f32x4*)(bias + s * 3072 + 2048 + col0 + bj * 128 + 4) + 1.0f; }
;             f32x4 xr[4][2];
;     ...
; #pragma unroll
;             for (int k = 0; k < 4; ++k) { xr[k][0] = *(const f32x4*)(xb + E3_OFF(k)); xr[k][1] = *(const f32x4*)(xb + E3_OFF(k) + 4); }
; #pragma unroll
;             for (int i = 0; i < 16; ++i) {
;                 const f32x4 x0 = xr[i & 3][0], x1 = xr[i & 3][1];
;                 if (i + 4 < 16) { xr[i & 3][0] = *(const f32x4*)(xb + E3_OFF(i + 4)); xr[i & 3][1] = *(const f32x4*)(xb + E3_OFF(i + 4) + 4); }
;                 const int ai = i >> 3, m = (i >> 1) & 3, bj = i & 1;
;                 *(f32x4*)(ob + E3_OFF(i)) = x0 * DN_ALPHA + gv[bj][0] * acc[ai][bj][m][0]; *(f32x4*)(ob + E3_OFF(i) + 4) = x1 * DN_ALPHA + gv[bj][1] * acc[ai][bj][m][1];
.LBB0_313:
	s_lshr_b32 s11, s36, 13
	s_ashr_i32 s10, s44, 12
	s_add_i32 s11, s11, 16
	s_and_b64 s[14:15], s[42:43], exec
	s_cselect_b32 s10, s10, s11
	v_mul_i32_i24_e32 v128, s10, v242
	v_ashrrev_i32_e32 v129, 31, v128
	v_readlane_b32 s10, v255, 31
	v_lshlrev_b64 v[128:129], 2, v[128:129]
	v_readlane_b32 s11, v255, 32
	v_ashrrev_i32_e32 v193, 31, v192
	v_lshlrev_b64 v[140:141], 2, v[192:193]
	v_lshl_add_u64 v[128:129], s[10:11], 0, v[128:129]
	v_lshl_add_u64 v[128:129], v[128:129], 0, v[140:141]
	s_mov_b64 s[14:15], 0x2000
	s_movk_i32 s10, 0x2000
	v_lshl_add_u64 v[136:137], v[128:129], 0, s[14:15]
	v_add_co_u32_e32 v128, vcc, s10, v128
	v_ashrrev_i32_e32 v169, 31, v168
	s_nop 0
	v_addc_co_u32_e32 v129, vcc, 0, v129, vcc
	global_load_dwordx4 v[128:131], v[128:129], off
	s_nop 0
	global_load_dwordx4 v[132:135], v[136:137], off offset:16
	v_lshl_add_u64 v[206:207], s[0:1], 0, v[140:141]
	v_lshlrev_b64 v[208:209], 12, v[168:169]
	v_lshl_add_u64 v[142:143], v[206:207], 0, v[208:209]
	s_mov_b64 s[0:1], 0x10000
	v_lshl_add_u64 v[166:167], v[208:209], 0, s[0:1]
	v_readlane_b32 s24, v255, 19
	v_readlane_b32 s26, v255, 21
	s_mov_b64 s[0:1], 0x20000
	v_readlane_b32 s27, v255, 22
	s_add_u32 s42, s26, s46
	v_lshl_add_u64 v[160:161], v[208:209], 0, s[0:1]
	s_addc_u32 s43, s27, s47
	v_lshl_add_u64 v[156:157], v[206:207], 0, v[160:161]
	v_lshl_add_u64 v[204:205], s[42:43], 0, v[140:141]
	v_lshl_add_u64 v[210:211], v[204:205], 0, v[208:209]
	s_mov_b64 s[0:1], 0x30000
	v_lshl_add_u64 v[160:161], v[204:205], 0, v[160:161]
	v_readlane_b32 s25, v255, 20
	v_readlane_b32 s28, v255, 23
	v_readlane_b32 s29, v255, 24
	v_readlane_b32 s30, v255, 25
	v_readlane_b32 s31, v255, 26
	s_mov_b32 s24, 0x3db504f3
	s_mov_b64 s[28:29], s[16:17]
	v_readlane_b32 s25, v255, 41
	s_mov_b32 s26, s40
	s_mov_b32 s27, s41
	s_mov_b32 s30, s48
	s_mov_b32 s31, s49
	s_waitcnt vmcnt(1)
	v_pk_add_f32 v[200:201], v[130:131], 1.0 op_sel_hi:[1,0]
	v_pk_add_f32 v[202:203], v[128:129], 1.0 op_sel_hi:[1,0]
	s_waitcnt vmcnt(0)
	v_pk_add_f32 v[196:197], v[134:135], 1.0 op_sel_hi:[1,0]
	v_pk_add_f32 v[198:199], v[132:133], 1.0 op_sel_hi:[1,0]
	global_load_dwordx4 v[128:131], v[136:137], off offset:528
	global_load_dwordx4 v[132:135], v[136:137], off offset:512
	s_waitcnt vmcnt(1)
	v_pk_add_f32 v[170:171], v[130:131], 1.0 op_sel_hi:[1,0]
	s_waitcnt vmcnt(0)
	v_pk_add_f32 v[174:175], v[134:135], 1.0 op_sel_hi:[1,0]
	v_pk_add_f32 v[194:195], v[132:133], 1.0 op_sel_hi:[1,0]
	v_pk_add_f32 v[172:173], v[128:129], 1.0 op_sel_hi:[1,0]
	global_load_dwordx4 v[128:131], v[142:143], off offset:16
	global_load_dwordx4 v[132:135], v[142:143], off
	global_load_dwordx4 v[136:139], v[142:143], off offset:528
	global_load_dwordx4 v[152:155], v[142:143], off offset:512
	v_lshl_add_u64 v[142:143], v[206:207], 0, v[166:167]
	global_load_dwordx4 v[162:165], v[142:143], off offset:16
	global_load_dwordx4 v[212:215], v[142:143], off
	global_load_dwordx4 v[218:221], v[142:143], off offset:528
	global_load_dwordx4 v[222:225], v[142:143], off offset:512
	s_nop 0
	global_load_dwordx4 v[140:143], v[156:157], off offset:16
	global_load_dwordx4 v[144:147], v[156:157], off
	v_lshl_add_u64 v[166:167], v[204:205], 0, v[166:167]
	s_waitcnt vmcnt(9)
	v_pk_mul_f32 v[130:131], v[130:131], s[76:77] op_sel_hi:[1,0]
	s_waitcnt vmcnt(8)
	v_pk_mul_f32 v[134:135], v[134:135], s[76:77] op_sel_hi:[1,0]
	v_pk_mul_f32 v[132:133], v[132:133], s[76:77] op_sel_hi:[1,0]
	v_pk_mul_f32 v[128:129], v[128:129], s[76:77] op_sel_hi:[1,0]
	v_pk_fma_f32 v[134:135], v[126:127], v[200:201], v[134:135]
	v_pk_fma_f32 v[132:133], v[124:125], v[202:203], v[132:133]
	v_pk_fma_f32 v[130:131], v[122:123], v[196:197], v[130:131]
	v_pk_fma_f32 v[128:129], v[120:121], v[198:199], v[128:129]
	global_store_dwordx4 v[210:211], v[132:135], off
	global_store_dwordx4 v[210:211], v[128:131], off offset:16
	global_load_dwordx4 v[148:151], v[156:157], off offset:528
	s_nop 0
	global_load_dwordx4 v[156:159], v[156:157], off offset:512
	s_waitcnt vmcnt(10)
	v_pk_mul_f32 v[128:129], v[154:155], s[76:77] op_sel_hi:[1,0]
	v_pk_mul_f32 v[132:133], v[152:153], s[76:77] op_sel_hi:[1,0]
	v_pk_fma_f32 v[130:131], v[62:63], v[174:175], v[128:129]
	v_pk_fma_f32 v[128:129], v[60:61], v[194:195], v[132:133]
	global_store_dwordx4 v[210:211], v[128:131], off offset:512
	v_pk_mul_f32 v[132:133], v[136:137], s[76:77] op_sel_hi:[1,0]
	s_waitcnt vmcnt(9)
	v_pk_mul_f32 v[154:155], v[212:213], s[76:77] op_sel_hi:[1,0]
	v_pk_mul_f32 v[128:129], v[138:139], s[76:77] op_sel_hi:[1,0]
	s_waitcnt vmcnt(7)
	v_pk_mul_f32 v[212:213], v[222:223], s[76:77] op_sel_hi:[1,0]
	v_pk_fma_f32 v[130:131], v[58:59], v[170:171], v[128:129]
	v_pk_fma_f32 v[128:129], v[56:57], v[172:173], v[132:133]
	global_store_dwordx4 v[210:211], v[128:131], off offset:528
	v_lshl_add_u64 v[210:211], v[208:209], 0, s[0:1]
	v_pk_mul_f32 v[132:133], v[214:215], s[76:77] op_sel_hi:[1,0]
	v_lshl_add_u64 v[152:153], v[206:207], 0, v[210:211]
	v_pk_fma_f32 v[134:135], v[118:119], v[200:201], v[132:133]
	v_pk_fma_f32 v[132:133], v[116:117], v[202:203], v[154:155]
	global_load_dwordx4 v[128:131], v[152:153], off offset:16
	global_load_dwordx4 v[136:139], v[152:153], off
	v_pk_mul_f32 v[154:155], v[162:163], s[76:77] op_sel_hi:[1,0]
	global_store_dwordx4 v[166:167], v[132:135], off
	v_pk_mul_f32 v[162:163], v[224:225], s[76:77] op_sel_hi:[1,0]
	s_mov_b64 s[0:1], 0x80000
	v_pk_mul_f32 v[132:133], v[164:165], s[76:77] op_sel_hi:[1,0]
	v_pk_fma_f32 v[164:165], v[54:55], v[174:175], v[162:163]
	v_pk_fma_f32 v[134:135], v[114:115], v[196:197], v[132:133]
	v_pk_fma_f32 v[132:133], v[112:113], v[198:199], v[154:155]
	global_store_dwordx4 v[166:167], v[132:135], off offset:16
	v_pk_fma_f32 v[162:163], v[52:53], v[194:195], v[212:213]
	global_load_dwordx4 v[132:135], v[152:153], off offset:528
	s_nop 0
	global_load_dwordx4 v[152:155], v[152:153], off offset:512
	v_pk_mul_f32 v[212:213], v[218:219], s[76:77] op_sel_hi:[1,0]
	global_store_dwordx4 v[166:167], v[162:165], off offset:512
	v_lshl_add_u64 v[214:215], v[208:209], 0, s[0:1]
	s_waitcnt vmcnt(13)
;     __device__ __forceinline__ void operator()(const f32x4 (&acc)[2][2][4][2], const pg8::Unit& u, int wr, int wc, int fr_in, int fq_in) const {
;     ...
;             for (int i = 0; i < 16; ++i) {
;                 const f32x4 x0 = xr[i & 3][0], x1 = xr[i & 3][1];
;                 if (i + 4 < 16) { xr[i & 3][0] = *(const f32x4*)(xb + E3_OFF(i + 4)); xr[i & 3][1] = *(const f32x4*)(xb + E3_OFF(i + 4) + 4); }
;                 const int ai = i >> 3, m = (i >> 1) & 3, bj = i & 1;
;                 *(f32x4*)(ob + E3_OFF(i)) = x0 * DN_ALPHA + gv[bj][0] * acc[ai][bj][m][0]; *(f32x4*)(ob + E3_OFF(i) + 4) = x1 * DN_ALPHA + gv[bj][1] * acc[ai][bj][m][1];
	v_pk_mul_f32 v[146:147], v[146:147], s[76:77] op_sel_hi:[1,0]
	v_pk_mul_f32 v[162:163], v[220:221], s[76:77] op_sel_hi:[1,0]
	v_pk_mul_f32 v[144:145], v[144:145], s[76:77] op_sel_hi:[1,0]
	v_pk_fma_f32 v[164:165], v[50:51], v[170:171], v[162:163]
	v_pk_fma_f32 v[162:163], v[48:49], v[172:173], v[212:213]
	global_store_dwordx4 v[166:167], v[162:165], off offset:528
	v_pk_mul_f32 v[142:143], v[142:143], s[76:77] op_sel_hi:[1,0]
	v_pk_mul_f32 v[140:141], v[140:141], s[76:77] op_sel_hi:[1,0]
	v_lshl_add_u64 v[162:163], v[206:207], 0, v[214:215]
	global_load_dwordx4 v[164:167], v[162:163], off offset:16
	global_load_dwordx4 v[218:221], v[162:163], off
	v_pk_fma_f32 v[146:147], v[110:111], v[200:201], v[146:147]
	v_pk_fma_f32 v[144:145], v[108:109], v[202:203], v[144:145]
	v_pk_fma_f32 v[142:143], v[106:107], v[196:197], v[142:143]
	v_pk_fma_f32 v[140:141], v[104:105], v[198:199], v[140:141]
	global_store_dwordx4 v[160:161], v[144:147], off
	global_store_dwordx4 v[160:161], v[140:143], off offset:16
	global_load_dwordx4 v[222:225], v[162:163], off offset:528
	global_load_dwordx4 v[226:229], v[162:163], off offset:512
	s_mov_b64 s[0:1], 0x90000
	v_lshl_add_u64 v[212:213], v[208:209], 0, s[0:1]
	s_mov_b64 s[0:1], 0xa0000
	v_lshl_add_u64 v[214:215], v[204:205], 0, v[214:215]
	s_waitcnt vmcnt(16)
	v_pk_mul_f32 v[140:141], v[158:159], s[76:77] op_sel_hi:[1,0]
	v_pk_mul_f32 v[144:145], v[156:157], s[76:77] op_sel_hi:[1,0]
	v_pk_fma_f32 v[142:143], v[46:47], v[174:175], v[140:141]
	v_pk_fma_f32 v[140:141], v[44:45], v[194:195], v[144:145]
	global_store_dwordx4 v[160:161], v[140:143], off offset:512
	v_pk_mul_f32 v[144:145], v[148:149], s[76:77] op_sel_hi:[1,0]
	v_lshl_add_u64 v[148:149], v[206:207], 0, v[212:213]
	v_pk_mul_f32 v[140:141], v[150:151], s[76:77] op_sel_hi:[1,0]
	v_lshl_add_u64 v[156:157], v[204:205], 0, v[210:211]
	v_pk_fma_f32 v[142:143], v[42:43], v[170:171], v[140:141]
	v_pk_fma_f32 v[140:141], v[40:41], v[172:173], v[144:145]
	global_store_dwordx4 v[160:161], v[140:143], off offset:528
	global_load_dwordx4 v[140:143], v[148:149], off offset:16
	s_nop 0
	global_load_dwordx4 v[160:163], v[148:149], off
	v_lshl_add_u64 v[210:211], v[208:209], 0, s[0:1]
	s_mov_b64 s[0:1], 0xb0000
	v_lshl_add_u64 v[208:209], v[208:209], 0, s[0:1]
	v_lshl_add_u64 v[212:213], v[204:205], 0, v[212:213]
	s_waitcnt vmcnt(17)
	v_pk_mul_f32 v[130:131], v[130:131], s[76:77] op_sel_hi:[1,0]
	s_waitcnt vmcnt(16)
	v_pk_mul_f32 v[138:139], v[138:139], s[76:77] op_sel_hi:[1,0]
	v_pk_mul_f32 v[136:137], v[136:137], s[76:77] op_sel_hi:[1,0]
	v_pk_mul_f32 v[128:129], v[128:129], s[76:77] op_sel_hi:[1,0]
	v_pk_fma_f32 v[138:139], v[102:103], v[200:201], v[138:139]
	v_pk_fma_f32 v[136:137], v[100:101], v[202:203], v[136:137]
	v_pk_fma_f32 v[130:131], v[98:99], v[196:197], v[130:131]
	v_pk_fma_f32 v[128:129], v[96:97], v[198:199], v[128:129]
	global_store_dwordx4 v[156:157], v[136:139], off
	global_store_dwordx4 v[156:157], v[128:131], off offset:16
	global_load_dwordx4 v[144:147], v[148:149], off offset:528
	s_nop 0
	global_load_dwordx4 v[148:151], v[148:149], off offset:512
	s_waitcnt vmcnt(17)
	v_pk_mul_f32 v[132:133], v[132:133], s[76:77] op_sel_hi:[1,0]
	s_waitcnt vmcnt(16)
	v_pk_mul_f32 v[128:129], v[154:155], s[76:77] op_sel_hi:[1,0]
	v_pk_mul_f32 v[136:137], v[152:153], s[76:77] op_sel_hi:[1,0]
	v_pk_fma_f32 v[130:131], v[38:39], v[174:175], v[128:129]
	v_pk_fma_f32 v[128:129], v[36:37], v[194:195], v[136:137]
	global_store_dwordx4 v[156:157], v[128:131], off offset:512
	v_lshl_add_u64 v[136:137], v[206:207], 0, v[210:211]
	v_lshl_add_u64 v[206:207], v[206:207], 0, v[208:209]
	v_pk_mul_f32 v[128:129], v[134:135], s[76:77] op_sel_hi:[1,0]
	s_mov_b64 s[0:1], 0
	v_pk_fma_f32 v[130:131], v[34:35], v[170:171], v[128:129]
	v_pk_fma_f32 v[128:129], v[32:33], v[172:173], v[132:133]
	global_store_dwordx4 v[156:157], v[128:131], off offset:528
	global_load_dwordx4 v[128:131], v[136:137], off offset:16
	s_nop 0
	global_load_dwordx4 v[152:155], v[136:137], off
	s_waitcnt vmcnt(16)
	v_pk_mul_f32 v[132:133], v[220:221], s[76:77] op_sel_hi:[1,0]
	v_pk_mul_f32 v[138:139], v[218:219], s[76:77] op_sel_hi:[1,0]
	v_pk_fma_f32 v[134:135], v[94:95], v[200:201], v[132:133]
	v_pk_fma_f32 v[132:133], v[92:93], v[202:203], v[138:139]
	global_store_dwordx4 v[214:215], v[132:135], off
	v_pk_mul_f32 v[138:139], v[164:165], s[76:77] op_sel_hi:[1,0]
	s_waitcnt vmcnt(13)
	v_pk_mul_f32 v[156:157], v[228:229], s[76:77] op_sel_hi:[1,0]
	v_pk_mul_f32 v[132:133], v[166:167], s[76:77] op_sel_hi:[1,0]
	v_pk_mul_f32 v[164:165], v[226:227], s[76:77] op_sel_hi:[1,0]
	v_pk_fma_f32 v[134:135], v[90:91], v[196:197], v[132:133]
	v_pk_fma_f32 v[132:133], v[88:89], v[198:199], v[138:139]
	global_store_dwordx4 v[214:215], v[132:135], off offset:16
	global_load_dwordx4 v[132:135], v[136:137], off offset:528
	s_nop 0
	global_load_dwordx4 v[136:139], v[136:137], off offset:512
	v_pk_fma_f32 v[158:159], v[30:31], v[174:175], v[156:157]
	v_pk_fma_f32 v[156:157], v[28:29], v[194:195], v[164:165]
	global_store_dwordx4 v[214:215], v[156:159], off offset:512
	v_pk_mul_f32 v[164:165], v[222:223], s[76:77] op_sel_hi:[1,0]
	s_waitcnt vmcnt(14)
	v_pk_mul_f32 v[142:143], v[142:143], s[76:77] op_sel_hi:[1,0]
	v_pk_mul_f32 v[156:157], v[224:225], s[76:77] op_sel_hi:[1,0]
	s_waitcnt vmcnt(13)
;     __device__ __forceinline__ void operator()(const f32x4 (&acc)[2][2][4][2], const pg8::Unit& u, int wr, int wc, int fr_in, int fq_in) const {
;     ...
;             for (int i = 0; i < 16; ++i) {
;                 const f32x4 x0 = xr[i & 3][0], x1 = xr[i & 3][1];
;                 if (i + 4 < 16) { xr[i & 3][0] = *(const f32x4*)(xb + E3_OFF(i + 4)); xr[i & 3][1] = *(const f32x4*)(xb + E3_OFF(i + 4) + 4); }
;                 const int ai = i >> 3, m = (i >> 1) & 3, bj = i & 1;
;                 *(f32x4*)(ob + E3_OFF(i)) = x0 * DN_ALPHA + gv[bj][0] * acc[ai][bj][m][0]; *(f32x4*)(ob + E3_OFF(i) + 4) = x1 * DN_ALPHA + gv[bj][1] * acc[ai][bj][m][1];
;             }
	v_pk_mul_f32 v[162:163], v[162:163], s[76:77] op_sel_hi:[1,0]
	v_pk_fma_f32 v[158:159], v[26:27], v[170:171], v[156:157]
	v_pk_fma_f32 v[156:157], v[24:25], v[172:173], v[164:165]
	global_store_dwordx4 v[214:215], v[156:159], off offset:528
	global_load_dwordx4 v[156:159], v[206:207], off offset:16
	s_nop 0
	global_load_dwordx4 v[164:167], v[206:207], off
	v_pk_mul_f32 v[160:161], v[160:161], s[76:77] op_sel_hi:[1,0]
	v_pk_mul_f32 v[140:141], v[140:141], s[76:77] op_sel_hi:[1,0]
	v_pk_fma_f32 v[162:163], v[86:87], v[200:201], v[162:163]
	v_pk_fma_f32 v[160:161], v[84:85], v[202:203], v[160:161]
	v_pk_fma_f32 v[142:143], v[82:83], v[196:197], v[142:143]
	v_pk_fma_f32 v[140:141], v[80:81], v[198:199], v[140:141]
	global_store_dwordx4 v[212:213], v[160:163], off
	global_store_dwordx4 v[212:213], v[140:143], off offset:16
	global_load_dwordx4 v[140:143], v[206:207], off offset:528
	s_nop 0
	global_load_dwordx4 v[160:163], v[206:207], off offset:512
	s_waitcnt vmcnt(16)
	v_pk_mul_f32 v[150:151], v[150:151], s[76:77] op_sel_hi:[1,0]
	v_pk_mul_f32 v[148:149], v[148:149], s[76:77] op_sel_hi:[1,0]
	v_pk_mul_f32 v[146:147], v[146:147], s[76:77] op_sel_hi:[1,0]
	v_pk_mul_f32 v[144:145], v[144:145], s[76:77] op_sel_hi:[1,0]
	v_pk_fma_f32 v[150:151], v[22:23], v[174:175], v[150:151]
	v_pk_fma_f32 v[148:149], v[20:21], v[194:195], v[148:149]
	v_pk_fma_f32 v[146:147], v[18:19], v[170:171], v[146:147]
	v_pk_fma_f32 v[144:145], v[16:17], v[172:173], v[144:145]
	global_store_dwordx4 v[212:213], v[148:151], off offset:512
	global_store_dwordx4 v[212:213], v[144:147], off offset:528
	s_waitcnt vmcnt(15)
	v_pk_mul_f32 v[130:131], v[130:131], s[76:77] op_sel_hi:[1,0]
	s_nop 0
	s_waitcnt vmcnt(14)
	v_pk_mul_f32 v[144:145], v[154:155], s[76:77] op_sel_hi:[1,0]
	v_pk_mul_f32 v[148:149], v[152:153], s[76:77] op_sel_hi:[1,0]
	v_pk_mul_f32 v[128:129], v[128:129], s[76:77] op_sel_hi:[1,0]
	v_pk_fma_f32 v[146:147], v[78:79], v[200:201], v[144:145]
	v_pk_fma_f32 v[144:145], v[76:77], v[202:203], v[148:149]
	v_lshl_add_u64 v[148:149], v[204:205], 0, v[210:211]
	v_pk_fma_f32 v[130:131], v[74:75], v[196:197], v[130:131]
	v_pk_fma_f32 v[128:129], v[72:73], v[198:199], v[128:129]
	global_store_dwordx4 v[148:149], v[128:131], off offset:16
	global_store_dwordx4 v[148:149], v[144:147], off
	s_waitcnt vmcnt(13)
	v_pk_mul_f32 v[132:133], v[132:133], s[76:77] op_sel_hi:[1,0]
	s_waitcnt vmcnt(12)
	v_pk_mul_f32 v[128:129], v[138:139], s[76:77] op_sel_hi:[1,0]
	v_pk_mul_f32 v[136:137], v[136:137], s[76:77] op_sel_hi:[1,0]
	v_pk_fma_f32 v[130:131], v[14:15], v[174:175], v[128:129]
	v_pk_fma_f32 v[128:129], v[12:13], v[194:195], v[136:137]
	global_store_dwordx4 v[148:149], v[128:131], off offset:512
	s_nop 1
	v_pk_mul_f32 v[128:129], v[134:135], s[76:77] op_sel_hi:[1,0]
	s_waitcnt vmcnt(10)
	v_pk_mul_f32 v[134:135], v[156:157], s[76:77] op_sel_hi:[1,0]
	v_pk_fma_f32 v[130:131], v[10:11], v[170:171], v[128:129]
	v_pk_fma_f32 v[128:129], v[8:9], v[172:173], v[132:133]
	global_store_dwordx4 v[148:149], v[128:131], off offset:528
	s_waitcnt vmcnt(10)
	v_pk_mul_f32 v[132:133], v[164:165], s[76:77] op_sel_hi:[1,0]
	s_nop 0
	v_pk_mul_f32 v[128:129], v[166:167], s[76:77] op_sel_hi:[1,0]
	s_nop 0
	v_pk_fma_f32 v[130:131], v[70:71], v[200:201], v[128:129]
	v_pk_fma_f32 v[128:129], v[68:69], v[202:203], v[132:133]
	v_lshl_add_u64 v[132:133], v[204:205], 0, v[208:209]
	global_store_dwordx4 v[132:133], v[128:131], off
	s_nop 1
	v_pk_mul_f32 v[128:129], v[158:159], s[76:77] op_sel_hi:[1,0]
	s_nop 0
	v_pk_fma_f32 v[130:131], v[66:67], v[196:197], v[128:129]
	v_pk_fma_f32 v[128:129], v[64:65], v[198:199], v[134:135]
	global_store_dwordx4 v[132:133], v[128:131], off offset:16
	s_waitcnt vmcnt(8)
	v_pk_mul_f32 v[134:135], v[160:161], s[76:77] op_sel_hi:[1,0]
	s_nop 0
	v_pk_mul_f32 v[128:129], v[162:163], s[76:77] op_sel_hi:[1,0]
	s_nop 0
	v_pk_fma_f32 v[130:131], v[6:7], v[174:175], v[128:129]
	v_pk_fma_f32 v[128:129], v[4:5], v[194:195], v[134:135]
	global_store_dwordx4 v[132:133], v[128:131], off offset:512
	v_pk_mul_f32 v[134:135], v[140:141], s[76:77] op_sel_hi:[1,0]
	s_nop 0
	v_pk_mul_f32 v[128:129], v[142:143], s[76:77] op_sel_hi:[1,0]
	s_nop 0
	v_pk_fma_f32 v[130:131], v[2:3], v[170:171], v[128:129]
	v_pk_fma_f32 v[128:129], v[0:1], v[172:173], v[134:135]
	global_store_dwordx4 v[132:133], v[128:131], off offset:528
; __device__ __forceinline__ unsigned cvt_pk_bf16(float lo, float hi) { unsigned r; asm("v_cvt_pk_bf16_f32 %0, %1, %2" : "=v"(r) : "v"(lo), "v"(hi)); return r; }
; __device__ __forceinline__ float bf_lo(unsigned u) { return __uint_as_float(u << 16); }
; __device__ __forceinline__ float bf_hi(unsigned u) { return __uint_as_float(u & 0xffff0000u); }
; #define E2_G(i) (C_MG + (E2_COL(i) >> 7) * 256 + 128 + (E2_COL(i) & 127))
;     __device__ __forceinline__ void operator()(const f32x4 (&acc)[2][2][4][2], const pg8::Unit& u, int wr, int wc, int fr_in, int fq_in) const {
;     ...
;             u32x4 gr[4];
;     ...
; #pragma unroll
;             for (int k = 0; k < 4; ++k) gr[k] = *(const u32x4*)(proj + E2_ROW(k) * NC1 + E2_G(k));
; #pragma unroll
;             for (int i = 0; i < 16; ++i) {
;                 const u32x4 ga = gr[i & 3];
;                 if (i + 4 < 16) gr[i & 3] = *(const u32x4*)(proj + E2_ROW(i + 4) * NC1 + E2_G(i + 4));
;                 const int ai = i >> 3, m = (i >> 1) & 3, bj = i & 1;
;                 f32x4 v0 = acc[ai][bj][m][0], v1 = acc[ai][bj][m][1];
;                 v0[0] *= bf_lo(ga.x); v0[1] *= bf_hi(ga.x); v0[2] *= bf_lo(ga.y); v0[3] *= bf_hi(ga.y);
;                 v1[0] *= bf_lo(ga.z); v1[1] *= bf_hi(ga.z); v1[2] *= bf_lo(ga.w); v1[3] *= bf_hi(ga.w);
;                 u32x4 w; w.x = cvt_pk_bf16(v0[0], v0[1]); w.y = cvt_pk_bf16(v0[2], v0[3]); w.z = cvt_pk_bf16(v1[0], v1[1]); w.w = cvt_pk_bf16(v1[2], v1[3]);
;                 *(u32x4*)(O + E2_ROW(i) * 1024 + E2_COL(i)) = w;
;             }
.LBB0_314:
	s_and_b64 vcc, exec, s[0:1]
	s_cbranch_vccz .LBB0_296
	v_add_u32_e32 v206, s9, v168
	s_cmp_lg_u32 s25, 0
	v_add_u32_e32 v210, 16, v206
	v_add_u32_e32 v208, 32, v206
	v_ashrrev_i32_e32 v193, 31, v192
	v_add_u32_e32 v204, 48, v206
	v_add_u32_e32 v200, 0x80, v206
	v_add_u32_e32 v198, 0x90, v206
	v_add_u32_e32 v196, 0xa0, v206
	v_add_u32_e32 v194, 0xb0, v206
	s_cbranch_scc0 .LBB0_317
	v_and_b32_e32 v128, 0x78, v176
	v_lshlrev_b32_e32 v135, 1, v192
	v_or_b32_e32 v134, 0x2080, v128
	v_and_b32_e32 v128, 0xffffff00, v135
	v_add_u32_e32 v128, v128, v134
	v_mov_b64_e32 v[150:151], s[98:99]
	v_ashrrev_i32_e32 v129, 31, v128
	v_mad_i64_i32 v[132:133], s[0:1], v206, s22, v[150:151]
	v_lshlrev_b64 v[152:153], 1, v[128:129]
	v_lshl_add_u64 v[128:129], v[132:133], 0, v[152:153]
	global_load_dwordx4 v[128:131], v[128:129], off
	v_add_u32_e32 v135, 0x100, v135
	v_and_b32_e32 v135, 0xffffff00, v135
	v_add_u32_e32 v134, v135, v134
	v_ashrrev_i32_e32 v135, 31, v134
	v_lshlrev_b64 v[148:149], 1, v[134:135]
	v_lshl_add_u64 v[132:133], v[132:133], 0, v[148:149]
	global_load_dwordx4 v[136:139], v[132:133], off
	v_mad_i64_i32 v[140:141], s[0:1], v210, s22, v[150:151]
	v_lshl_add_u64 v[132:133], v[140:141], 0, v[152:153]
	global_load_dwordx4 v[132:135], v[132:133], off
	v_lshl_add_u64 v[140:141], v[140:141], 0, v[148:149]
	global_load_dwordx4 v[140:143], v[140:141], off
	v_mad_i64_i32 v[156:157], s[0:1], v208, s22, v[150:151]
	v_lshl_add_u64 v[144:145], v[156:157], 0, v[152:153]
	global_load_dwordx4 v[144:147], v[144:145], off
	v_ashrrev_i32_e32 v207, 31, v206
	v_ashrrev_i32_e32 v211, 31, v210
	v_ashrrev_i32_e32 v209, 31, v208
	v_ashrrev_i32_e32 v205, 31, v204
	v_ashrrev_i32_e32 v201, 31, v200
	v_ashrrev_i32_e32 v199, 31, v198
	v_ashrrev_i32_e32 v197, 31, v196
	v_ashrrev_i32_e32 v195, 31, v194
	s_waitcnt vmcnt(4)
	v_lshlrev_b32_e32 v154, 16, v128
	v_and_b32_e32 v128, 0xffff0000, v128
	v_lshlrev_b32_e32 v155, 16, v129
	v_and_b32_e32 v129, 0xffff0000, v129
	v_mul_f32_e32 v154, v124, v154
	v_mul_f32_e32 v128, v125, v128
	v_mul_f32_e32 v155, v126, v155
	v_mul_f32_e32 v129, v127, v129
	v_lshlrev_b32_e32 v158, 16, v130
	v_and_b32_e32 v130, 0xffff0000, v130
	v_lshlrev_b32_e32 v159, 16, v131
	v_and_b32_e32 v131, 0xffff0000, v131
	v_mul_f32_e32 v158, v120, v158
	v_mul_f32_e32 v130, v121, v130
	v_mul_f32_e32 v159, v122, v159
	v_mul_f32_e32 v131, v123, v131
	v_cvt_pk_bf16_f32 v128, v154, v128
	v_cvt_pk_bf16_f32 v129, v155, v129
	v_lshlrev_b64 v[154:155], 11, v[206:207]
	v_cvt_pk_bf16_f32 v130, v158, v130
	v_cvt_pk_bf16_f32 v131, v159, v131
	v_lshl_add_u64 v[158:159], s[50:51], 0, v[154:155]
	v_lshlrev_b64 v[154:155], 1, v[192:193]
	v_lshl_add_u64 v[158:159], v[158:159], 0, v[154:155]
	global_store_dwordx4 v[158:159], v[128:131], off
	s_waitcnt vmcnt(4)
	v_lshlrev_b32_e32 v160, 16, v138
	v_and_b32_e32 v138, 0xffff0000, v138
	v_lshl_add_u64 v[128:129], v[156:157], 0, v[148:149]
	global_load_dwordx4 v[128:131], v[128:129], off
	v_lshlrev_b32_e32 v156, 16, v136
	v_and_b32_e32 v136, 0xffff0000, v136
	v_lshlrev_b32_e32 v157, 16, v137
	v_and_b32_e32 v137, 0xffff0000, v137
	v_mul_f32_e32 v156, v60, v156
	v_mul_f32_e32 v136, v61, v136
	v_mul_f32_e32 v157, v62, v157
	v_mul_f32_e32 v137, v63, v137
	v_lshlrev_b32_e32 v161, 16, v139
	v_and_b32_e32 v139, 0xffff0000, v139
	v_mul_f32_e32 v138, v57, v138
	v_mul_f32_e32 v139, v59, v139
	v_cvt_pk_bf16_f32 v136, v156, v136
	v_cvt_pk_bf16_f32 v137, v157, v137
	v_mad_i64_i32 v[156:157], s[0:1], v204, s22, v[150:151]
	v_mul_f32_e32 v160, v56, v160
	v_mul_f32_e32 v161, v58, v161
	v_cvt_pk_bf16_f32 v138, v160, v138
	v_cvt_pk_bf16_f32 v139, v161, v139
	global_store_dwordx4 v[158:159], v[136:139], off offset:256
	s_waitcnt vmcnt(5)
	v_lshlrev_b32_e32 v158, 16, v132
	v_and_b32_e32 v132, 0xffff0000, v132
	v_lshl_add_u64 v[136:137], v[156:157], 0, v[152:153]
	v_lshlrev_b32_e32 v159, 16, v133
	v_and_b32_e32 v133, 0xffff0000, v133
	global_load_dwordx4 v[136:139], v[136:137], off
	v_mul_f32_e32 v158, v116, v158
	v_mul_f32_e32 v132, v117, v132
	v_mul_f32_e32 v159, v118, v159
	v_mul_f32_e32 v133, v119, v133
	v_cvt_pk_bf16_f32 v132, v158, v132
	v_cvt_pk_bf16_f32 v133, v159, v133
	v_lshlrev_b64 v[158:159], 11, v[210:211]
	v_lshlrev_b32_e32 v160, 16, v134
	v_and_b32_e32 v134, 0xffff0000, v134
	v_lshlrev_b32_e32 v161, 16, v135
	v_and_b32_e32 v135, 0xffff0000, v135
	v_lshl_add_u64 v[158:159], s[50:51], 0, v[158:159]
	v_mul_f32_e32 v160, v112, v160
	v_mul_f32_e32 v134, v113, v134
	v_mul_f32_e32 v161, v114, v161
	v_mul_f32_e32 v135, v115, v135
	v_lshl_add_u64 v[158:159], v[158:159], 0, v[154:155]
	v_cvt_pk_bf16_f32 v134, v160, v134
	v_cvt_pk_bf16_f32 v135, v161, v135
	global_store_dwordx4 v[158:159], v[132:135], off
	s_waitcnt vmcnt(6)
	v_lshlrev_b32_e32 v160, 16, v142
	v_and_b32_e32 v142, 0xffff0000, v142
	v_lshl_add_u64 v[132:133], v[156:157], 0, v[148:149]
	v_lshlrev_b32_e32 v156, 16, v140
	v_and_b32_e32 v140, 0xffff0000, v140
	v_lshlrev_b32_e32 v157, 16, v141
	v_and_b32_e32 v141, 0xffff0000, v141
	v_lshlrev_b32_e32 v161, 16, v143
	v_and_b32_e32 v143, 0xffff0000, v143
	global_load_dwordx4 v[132:135], v[132:133], off
	v_mul_f32_e32 v156, v52, v156
	v_mul_f32_e32 v140, v53, v140
	v_mul_f32_e32 v157, v54, v157
	v_mul_f32_e32 v141, v55, v141
	v_mul_f32_e32 v160, v48, v160
	v_mul_f32_e32 v142, v49, v142
	v_mul_f32_e32 v161, v50, v161
	v_mul_f32_e32 v143, v51, v143
	v_cvt_pk_bf16_f32 v140, v156, v140
	v_cvt_pk_bf16_f32 v141, v157, v141
	v_cvt_pk_bf16_f32 v142, v160, v142
	v_cvt_pk_bf16_f32 v143, v161, v143
	v_mad_i64_i32 v[160:161], s[0:1], v200, s22, v[150:151]
	s_waitcnt vmcnt(6)
; __device__ __forceinline__ unsigned cvt_pk_bf16(float lo, float hi) { unsigned r; asm("v_cvt_pk_bf16_f32 %0, %1, %2" : "=v"(r) : "v"(lo), "v"(hi)); return r; }
; __device__ __forceinline__ float bf_lo(unsigned u) { return __uint_as_float(u << 16); }
; __device__ __forceinline__ float bf_hi(unsigned u) { return __uint_as_float(u & 0xffff0000u); }
; #define E2_G(i) (C_MG + (E2_COL(i) >> 7) * 256 + 128 + (E2_COL(i) & 127))
;     __device__ __forceinline__ void operator()(const f32x4 (&acc)[2][2][4][2], const pg8::Unit& u, int wr, int wc, int fr_in, int fq_in) const {
;     ...
;             for (int i = 0; i < 16; ++i) {
;                 const u32x4 ga = gr[i & 3];
;                 if (i + 4 < 16) gr[i & 3] = *(const u32x4*)(proj + E2_ROW(i + 4) * NC1 + E2_G(i + 4));
;                 const int ai = i >> 3, m = (i >> 1) & 3, bj = i & 1;
;                 f32x4 v0 = acc[ai][bj][m][0], v1 = acc[ai][bj][m][1];
;                 v0[0] *= bf_lo(ga.x); v0[1] *= bf_hi(ga.x); v0[2] *= bf_lo(ga.y); v0[3] *= bf_hi(ga.y);
;                 v1[0] *= bf_lo(ga.z); v1[1] *= bf_hi(ga.z); v1[2] *= bf_lo(ga.w); v1[3] *= bf_hi(ga.w);
;                 u32x4 w; w.x = cvt_pk_bf16(v0[0], v0[1]); w.y = cvt_pk_bf16(v0[2], v0[3]); w.z = cvt_pk_bf16(v1[0], v1[1]); w.w = cvt_pk_bf16(v1[2], v1[3]);
;                 *(u32x4*)(O + E2_ROW(i) * 1024 + E2_COL(i)) = w;
;             }
	v_lshlrev_b32_e32 v156, 16, v144
	v_and_b32_e32 v144, 0xffff0000, v144
	v_lshlrev_b32_e32 v157, 16, v145
	v_and_b32_e32 v145, 0xffff0000, v145
	global_store_dwordx4 v[158:159], v[140:143], off offset:256
	v_mul_f32_e32 v156, v108, v156
	v_mul_f32_e32 v144, v109, v144
	v_lshl_add_u64 v[140:141], v[160:161], 0, v[152:153]
	v_mul_f32_e32 v157, v110, v157
	v_mul_f32_e32 v145, v111, v145
	global_load_dwordx4 v[140:143], v[140:141], off
	v_cvt_pk_bf16_f32 v156, v156, v144
	v_cvt_pk_bf16_f32 v157, v157, v145
	v_lshlrev_b64 v[144:145], 11, v[208:209]
	v_lshlrev_b32_e32 v158, 16, v146
	v_and_b32_e32 v146, 0xffff0000, v146
	v_lshlrev_b32_e32 v159, 16, v147
	v_and_b32_e32 v147, 0xffff0000, v147
	v_lshl_add_u64 v[144:145], s[50:51], 0, v[144:145]
	v_mul_f32_e32 v158, v104, v158
	v_mul_f32_e32 v146, v105, v146
	v_mul_f32_e32 v159, v106, v159
	v_mul_f32_e32 v147, v107, v147
	v_lshl_add_u64 v[144:145], v[144:145], 0, v[154:155]
	v_cvt_pk_bf16_f32 v158, v158, v146
	v_cvt_pk_bf16_f32 v159, v159, v147
	global_store_dwordx4 v[144:145], v[156:159], off
	v_lshl_add_u64 v[146:147], v[160:161], 0, v[148:149]
	global_load_dwordx4 v[156:159], v[146:147], off
	s_waitcnt vmcnt(8)
	v_lshlrev_b32_e32 v146, 16, v128
	v_and_b32_e32 v128, 0xffff0000, v128
	v_lshlrev_b32_e32 v147, 16, v129
	v_and_b32_e32 v129, 0xffff0000, v129
	v_lshlrev_b32_e32 v160, 16, v130
	v_and_b32_e32 v130, 0xffff0000, v130
	v_lshlrev_b32_e32 v161, 16, v131
	v_and_b32_e32 v131, 0xffff0000, v131
	v_mul_f32_e32 v128, v45, v128
	v_mul_f32_e32 v129, v47, v129
	v_mul_f32_e32 v130, v41, v130
	v_mul_f32_e32 v131, v43, v131
	v_mul_f32_e32 v146, v44, v146
	v_mul_f32_e32 v147, v46, v147
	v_mul_f32_e32 v160, v40, v160
	v_mul_f32_e32 v161, v42, v161
	v_cvt_pk_bf16_f32 v128, v146, v128
	v_cvt_pk_bf16_f32 v129, v147, v129
	v_cvt_pk_bf16_f32 v130, v160, v130
	v_cvt_pk_bf16_f32 v131, v161, v131
	global_store_dwordx4 v[144:145], v[128:131], off offset:256
	v_mad_i64_i32 v[144:145], s[0:1], v198, s22, v[150:151]
	s_nop 0
	v_lshl_add_u64 v[128:129], v[144:145], 0, v[152:153]
	global_load_dwordx4 v[128:131], v[128:129], off
	s_waitcnt vmcnt(8)
	v_lshlrev_b32_e32 v146, 16, v136
	v_and_b32_e32 v136, 0xffff0000, v136
	v_lshlrev_b32_e32 v147, 16, v137
	v_and_b32_e32 v137, 0xffff0000, v137
	v_mul_f32_e32 v146, v100, v146
	v_mul_f32_e32 v136, v101, v136
	v_mul_f32_e32 v147, v102, v147
	v_mul_f32_e32 v137, v103, v137
	v_cvt_pk_bf16_f32 v136, v146, v136
	v_cvt_pk_bf16_f32 v137, v147, v137
	v_lshlrev_b64 v[146:147], 11, v[204:205]
	v_lshlrev_b32_e32 v160, 16, v138
	v_and_b32_e32 v138, 0xffff0000, v138
	v_lshlrev_b32_e32 v161, 16, v139
	v_and_b32_e32 v139, 0xffff0000, v139
	v_lshl_add_u64 v[146:147], s[50:51], 0, v[146:147]
	v_mul_f32_e32 v138, v97, v138
	v_mul_f32_e32 v139, v99, v139
	v_lshl_add_u64 v[146:147], v[146:147], 0, v[154:155]
	v_mul_f32_e32 v160, v96, v160
	v_mul_f32_e32 v161, v98, v161
	v_cvt_pk_bf16_f32 v138, v160, v138
	v_cvt_pk_bf16_f32 v139, v161, v139
	global_store_dwordx4 v[146:147], v[136:139], off
	s_waitcnt vmcnt(7)
	v_lshlrev_b32_e32 v160, 16, v134
	v_and_b32_e32 v134, 0xffff0000, v134
	v_lshl_add_u64 v[136:137], v[144:145], 0, v[148:149]
	v_lshlrev_b32_e32 v144, 16, v132
	v_and_b32_e32 v132, 0xffff0000, v132
	v_lshlrev_b32_e32 v145, 16, v133
	v_and_b32_e32 v133, 0xffff0000, v133
	global_load_dwordx4 v[136:139], v[136:137], off
	v_mul_f32_e32 v144, v36, v144
	v_mul_f32_e32 v132, v37, v132
	v_mul_f32_e32 v145, v38, v145
	v_mul_f32_e32 v133, v39, v133
	v_lshlrev_b32_e32 v161, 16, v135
	v_and_b32_e32 v135, 0xffff0000, v135
	v_mul_f32_e32 v134, v33, v134
	v_mul_f32_e32 v135, v35, v135
	v_cvt_pk_bf16_f32 v132, v144, v132
	v_cvt_pk_bf16_f32 v133, v145, v133
	v_mad_i64_i32 v[144:145], s[0:1], v196, s22, v[150:151]
	v_mul_f32_e32 v160, v32, v160
	v_mul_f32_e32 v161, v34, v161
	v_cvt_pk_bf16_f32 v134, v160, v134
	v_cvt_pk_bf16_f32 v135, v161, v135
	global_store_dwordx4 v[146:147], v[132:135], off offset:256
	s_waitcnt vmcnt(7)
	v_lshlrev_b32_e32 v146, 16, v140
	v_and_b32_e32 v140, 0xffff0000, v140
	v_lshl_add_u64 v[132:133], v[144:145], 0, v[152:153]
	v_lshlrev_b32_e32 v147, 16, v141
	v_and_b32_e32 v141, 0xffff0000, v141
	global_load_dwordx4 v[132:135], v[132:133], off
	v_mul_f32_e32 v146, v92, v146
	v_mul_f32_e32 v140, v93, v140
	v_mul_f32_e32 v147, v94, v147
	v_mul_f32_e32 v141, v95, v141
	v_lshlrev_b32_e32 v160, 16, v142
	v_and_b32_e32 v142, 0xffff0000, v142
	v_lshlrev_b32_e32 v161, 16, v143
	v_and_b32_e32 v143, 0xffff0000, v143
	v_cvt_pk_bf16_f32 v140, v146, v140
	v_cvt_pk_bf16_f32 v141, v147, v141
	v_lshlrev_b64 v[146:147], 11, v[200:201]
	v_mul_f32_e32 v160, v88, v160
	v_mul_f32_e32 v142, v89, v142
	v_mul_f32_e32 v161, v90, v161
	v_mul_f32_e32 v143, v91, v143
	v_lshl_add_u64 v[146:147], s[50:51], 0, v[146:147]
	v_cvt_pk_bf16_f32 v142, v160, v142
	v_cvt_pk_bf16_f32 v143, v161, v143
	v_lshl_add_u64 v[160:161], v[146:147], 0, v[154:155]
	global_store_dwordx4 v[160:161], v[140:143], off
	s_waitcnt vmcnt(7)
	v_lshlrev_b32_e32 v146, 16, v157
	v_and_b32_e32 v147, 0xffff0000, v157
	v_lshl_add_u64 v[140:141], v[144:145], 0, v[148:149]
	v_lshlrev_b32_e32 v144, 16, v156
	v_and_b32_e32 v145, 0xffff0000, v156
	global_load_dwordx4 v[140:143], v[140:141], off
	v_mul_f32_e32 v144, v28, v144
	v_mul_f32_e32 v145, v29, v145
	v_mul_f32_e32 v146, v30, v146
	v_mul_f32_e32 v147, v31, v147
	v_lshlrev_b32_e32 v156, 16, v158
	v_and_b32_e32 v157, 0xffff0000, v158
	v_lshlrev_b32_e32 v158, 16, v159
	v_and_b32_e32 v159, 0xffff0000, v159
	v_cvt_pk_bf16_f32 v144, v144, v145
	v_cvt_pk_bf16_f32 v145, v146, v147
	v_mad_i64_i32 v[150:151], s[0:1], v194, s22, v[150:151]
	v_mul_f32_e32 v156, v24, v156
	v_mul_f32_e32 v157, v25, v157
	v_mul_f32_e32 v158, v26, v158
	v_mul_f32_e32 v159, v27, v159
	v_cvt_pk_bf16_f32 v146, v156, v157
	v_cvt_pk_bf16_f32 v147, v158, v159
	global_store_dwordx4 v[160:161], v[144:147], off offset:256
	s_waitcnt vmcnt(7)
; __device__ __forceinline__ unsigned cvt_pk_bf16(float lo, float hi) { unsigned r; asm("v_cvt_pk_bf16_f32 %0, %1, %2" : "=v"(r) : "v"(lo), "v"(hi)); return r; }
; __device__ __forceinline__ float bf_lo(unsigned u) { return __uint_as_float(u << 16); }
; __device__ __forceinline__ float bf_hi(unsigned u) { return __uint_as_float(u & 0xffff0000u); }
; #define E2_G(i) (C_MG + (E2_COL(i) >> 7) * 256 + 128 + (E2_COL(i) & 127))
;     __device__ __forceinline__ void operator()(const f32x4 (&acc)[2][2][4][2], const pg8::Unit& u, int wr, int wc, int fr_in, int fq_in) const {
;     ...
;             for (int i = 0; i < 16; ++i) {
;                 const u32x4 ga = gr[i & 3];
;                 if (i + 4 < 16) gr[i & 3] = *(const u32x4*)(proj + E2_ROW(i + 4) * NC1 + E2_G(i + 4));
;                 const int ai = i >> 3, m = (i >> 1) & 3, bj = i & 1;
;                 f32x4 v0 = acc[ai][bj][m][0], v1 = acc[ai][bj][m][1];
;                 v0[0] *= bf_lo(ga.x); v0[1] *= bf_hi(ga.x); v0[2] *= bf_lo(ga.y); v0[3] *= bf_hi(ga.y);
;                 v1[0] *= bf_lo(ga.z); v1[1] *= bf_hi(ga.z); v1[2] *= bf_lo(ga.w); v1[3] *= bf_hi(ga.w);
;                 u32x4 w; w.x = cvt_pk_bf16(v0[0], v0[1]); w.y = cvt_pk_bf16(v0[2], v0[3]); w.z = cvt_pk_bf16(v1[0], v1[1]); w.w = cvt_pk_bf16(v1[2], v1[3]);
;                 *(u32x4*)(O + E2_ROW(i) * 1024 + E2_COL(i)) = w;
;             }
	v_lshlrev_b32_e32 v156, 16, v130
	v_and_b32_e32 v130, 0xffff0000, v130
	v_lshl_add_u64 v[144:145], v[150:151], 0, v[152:153]
	v_lshlrev_b32_e32 v152, 16, v128
	v_and_b32_e32 v128, 0xffff0000, v128
	v_lshlrev_b32_e32 v153, 16, v129
	v_and_b32_e32 v129, 0xffff0000, v129
	global_load_dwordx4 v[144:147], v[144:145], off
	v_mul_f32_e32 v152, v84, v152
	v_mul_f32_e32 v128, v85, v128
	v_mul_f32_e32 v153, v86, v153
	v_mul_f32_e32 v129, v87, v129
	v_cvt_pk_bf16_f32 v128, v152, v128
	v_cvt_pk_bf16_f32 v129, v153, v129
	v_lshlrev_b64 v[152:153], 11, v[198:199]
	v_lshlrev_b32_e32 v157, 16, v131
	v_and_b32_e32 v131, 0xffff0000, v131
	v_lshl_add_u64 v[152:153], s[50:51], 0, v[152:153]
	v_mul_f32_e32 v130, v81, v130
	v_mul_f32_e32 v131, v83, v131
	v_lshl_add_u64 v[152:153], v[152:153], 0, v[154:155]
	v_mul_f32_e32 v156, v80, v156
	v_mul_f32_e32 v157, v82, v157
	v_cvt_pk_bf16_f32 v130, v156, v130
	v_cvt_pk_bf16_f32 v131, v157, v131
	global_store_dwordx4 v[152:153], v[128:131], off
	s_nop 1
	v_lshl_add_u64 v[128:129], v[150:151], 0, v[148:149]
	global_load_dwordx4 v[128:131], v[128:129], off
	s_waitcnt vmcnt(8)
	v_lshlrev_b32_e32 v148, 16, v136
	v_and_b32_e32 v136, 0xffff0000, v136
	v_lshlrev_b32_e32 v149, 16, v137
	v_and_b32_e32 v137, 0xffff0000, v137
	v_mul_f32_e32 v136, v21, v136
	v_mul_f32_e32 v137, v23, v137
	v_lshlrev_b32_e32 v150, 16, v138
	v_and_b32_e32 v138, 0xffff0000, v138
	v_lshlrev_b32_e32 v151, 16, v139
	v_and_b32_e32 v139, 0xffff0000, v139
	v_mul_f32_e32 v148, v20, v148
	v_mul_f32_e32 v149, v22, v149
	v_mul_f32_e32 v138, v17, v138
	v_mul_f32_e32 v139, v19, v139
	v_cvt_pk_bf16_f32 v136, v148, v136
	v_cvt_pk_bf16_f32 v137, v149, v137
	v_mul_f32_e32 v150, v16, v150
	v_mul_f32_e32 v151, v18, v151
	v_cvt_pk_bf16_f32 v138, v150, v138
	v_cvt_pk_bf16_f32 v139, v151, v139
	global_store_dwordx4 v[152:153], v[136:139], off offset:256
	s_nop 1
	s_waitcnt vmcnt(7)
	v_lshlrev_b32_e32 v136, 16, v132
	v_and_b32_e32 v132, 0xffff0000, v132
	v_lshlrev_b32_e32 v137, 16, v133
	v_and_b32_e32 v133, 0xffff0000, v133
	v_mul_f32_e32 v136, v76, v136
	v_mul_f32_e32 v132, v77, v132
	v_mul_f32_e32 v137, v78, v137
	v_mul_f32_e32 v133, v79, v133
	v_lshlrev_b32_e32 v138, 16, v134
	v_and_b32_e32 v134, 0xffff0000, v134
	v_cvt_pk_bf16_f32 v132, v136, v132
	v_cvt_pk_bf16_f32 v133, v137, v133
	v_lshlrev_b64 v[136:137], 11, v[196:197]
	v_mul_f32_e32 v134, v73, v134
	v_lshlrev_b32_e32 v139, 16, v135
	v_and_b32_e32 v135, 0xffff0000, v135
	v_lshl_add_u64 v[136:137], s[50:51], 0, v[136:137]
	v_mul_f32_e32 v138, v72, v138
	v_mul_f32_e32 v135, v75, v135
	v_cvt_pk_bf16_f32 v134, v138, v134
	v_lshl_add_u64 v[136:137], v[136:137], 0, v[154:155]
	v_mul_f32_e32 v139, v74, v139
	v_cvt_pk_bf16_f32 v135, v139, v135
	global_store_dwordx4 v[136:137], v[132:135], off
	s_waitcnt vmcnt(6)
	v_lshlrev_b32_e32 v138, 16, v142
	v_and_b32_e32 v139, 0xffff0000, v142
	v_lshlrev_b32_e32 v132, 16, v140
	v_and_b32_e32 v133, 0xffff0000, v140
	v_lshlrev_b32_e32 v134, 16, v141
	v_mul_f32_e32 v132, v12, v132
	v_mul_f32_e32 v133, v13, v133
	v_mul_f32_e32 v134, v14, v134
	v_and_b32_e32 v135, 0xffff0000, v141
	v_mul_f32_e32 v135, v15, v135
	v_mul_f32_e32 v138, v8, v138
	v_mul_f32_e32 v139, v9, v139
	v_lshlrev_b32_e32 v140, 16, v143
	v_and_b32_e32 v141, 0xffff0000, v143
	v_cvt_pk_bf16_f32 v132, v132, v133
	v_cvt_pk_bf16_f32 v133, v134, v135
	v_cvt_pk_bf16_f32 v134, v138, v139
	v_mul_f32_e32 v140, v10, v140
	v_mul_f32_e32 v141, v11, v141
	v_cvt_pk_bf16_f32 v135, v140, v141
	global_store_dwordx4 v[136:137], v[132:135], off offset:256
	s_waitcnt vmcnt(5)
	v_lshlrev_b32_e32 v136, 16, v146
	v_and_b32_e32 v137, 0xffff0000, v146
	v_lshlrev_b32_e32 v132, 16, v144
	v_and_b32_e32 v133, 0xffff0000, v144
	v_lshlrev_b32_e32 v134, 16, v145
	v_mul_f32_e32 v132, v68, v132
	v_mul_f32_e32 v133, v69, v133
	v_mul_f32_e32 v134, v70, v134
	v_and_b32_e32 v135, 0xffff0000, v145
	v_mul_f32_e32 v136, v64, v136
	v_mul_f32_e32 v137, v65, v137
	v_mul_f32_e32 v135, v71, v135
	v_cvt_pk_bf16_f32 v132, v132, v133
	v_cvt_pk_bf16_f32 v133, v134, v135
	v_cvt_pk_bf16_f32 v134, v136, v137
	v_lshlrev_b64 v[136:137], 11, v[194:195]
	v_lshlrev_b32_e32 v138, 16, v147
	v_and_b32_e32 v139, 0xffff0000, v147
	v_lshl_add_u64 v[136:137], s[50:51], 0, v[136:137]
	v_mul_f32_e32 v138, v66, v138
	v_mul_f32_e32 v139, v67, v139
	v_cvt_pk_bf16_f32 v135, v138, v139
	v_lshl_add_u64 v[136:137], v[136:137], 0, v[154:155]
	global_store_dwordx4 v[136:137], v[132:135], off
	s_nop 1
	s_waitcnt vmcnt(4)
	v_lshlrev_b32_e32 v132, 16, v128
	v_and_b32_e32 v128, 0xffff0000, v128
	v_lshlrev_b32_e32 v133, 16, v129
	v_and_b32_e32 v129, 0xffff0000, v129
	v_lshlrev_b32_e32 v134, 16, v130
	v_and_b32_e32 v130, 0xffff0000, v130
	v_lshlrev_b32_e32 v135, 16, v131
	v_and_b32_e32 v131, 0xffff0000, v131
	v_mul_f32_e32 v128, v5, v128
	v_mul_f32_e32 v129, v7, v129
	v_mul_f32_e32 v130, v1, v130
	v_mul_f32_e32 v131, v3, v131
	v_mul_f32_e32 v132, v4, v132
	v_mul_f32_e32 v133, v6, v133
	v_mul_f32_e32 v134, v0, v134
	v_mul_f32_e32 v135, v2, v135
	v_cvt_pk_bf16_f32 v128, v132, v128
	v_cvt_pk_bf16_f32 v129, v133, v129
	v_cvt_pk_bf16_f32 v130, v134, v130
	v_cvt_pk_bf16_f32 v131, v135, v131
	global_store_dwordx4 v[136:137], v[128:131], off offset:256
	s_cbranch_execnz .LBB0_296
	s_branch .LBB0_318
